# v89 + hgC preamble draws both initial ids with one returning atomic
# speedup vs baseline: 1.0267x; 1.0039x over previous
; __device__ __forceinline__ void hgC_loop(Frame& F, unsigned* ctr) {
;     ...
;     if (tid == 0) { slot[0] = (int)__hip_atomic_fetch_add(ctr, 1u, __ATOMIC_RELAXED, __HIP_MEMORY_SCOPE_AGENT); slot[1] = (int)__hip_atomic_fetch_add(ctr, 1u, __ATOMIC_RELAXED, __HIP_MEMORY_SCOPE_AGENT); }
;     __syncthreads();
;     int item = slot[0], nxt = slot[1], par = 0;
.LBB0_684:
	s_add_u32 s4, s50, 0x8000
	s_addc_u32 s5, s51, 0
	s_and_b32 s3, s2, 7
	s_lshl_b32 s30, s3, 7
	s_lshl_b32 s3, s3, 8
	s_add_u32 s4, s4, s3
	s_addc_u32 s5, s5, 0
	v_mov_b32_e32 v235, 0x400
	s_waitcnt vmcnt(0)
	s_barrier
	s_and_saveexec_b64 s[0:1], s[92:93]
	s_cbranch_execz .LBB0_690
	v_mov_b32_e32 v2, 0
	v_mov_b32_e32 v4, 2
	global_atomic_add v3, v2, v4, s[4:5] sc0
	s_waitcnt vmcnt(0)
	v_add_u32_e32 v4, 1, v3
	v_cmp_gt_u32_e32 vcc, 0x80, v3
	v_add_u32_e32 v3, s30, v3
	s_nop 1
	v_cndmask_b32_e32 v3, v235, v3, vcc
	ds_write_b32 v2, v3 offset:53248
	v_cmp_gt_u32_e32 vcc, 0x80, v4
	v_add_u32_e32 v4, s30, v4
	s_nop 1
	v_cndmask_b32_e32 v4, v235, v4, vcc
	ds_write_b32 v2, v4 offset:53252
